# v15 with the fragment reads issued first after each barrier in the steady-state differential-attention loops (staging stores / next loads behind them, lgkmcnt waits re-derived)
# baseline (speedup 1.0000x reference)
.Lfast_e1:
	s_barrier
	ds_read_b128 v[112:115], v213 offset:9216
	ds_read_b128 v[128:131], v213 offset:9248
	ds_read_b128 v[132:135], v213 offset:13824
	ds_read_b128 v[136:139], v213 offset:13856
	s_waitcnt vmcnt(0)
	ds_write_b128 v211, v[192:195]
	s_waitcnt vmcnt(1)
	ds_write_b128 v210, v[196:199] offset:36864
	s_waitcnt vmcnt(0)
	ds_write_b128 v212, v[200:203] offset:36864
	s_add_i32 s4, s52, 0xfffff000
	s_and_b32 s4, s4, 0x7f000
	s_lshl_b32 s8, s4, 1
	v_lshl_add_u64 v[254:255], v[216:217], 0, s[8:9]
	global_load_dwordx4 v[192:195], v[254:255], off
	s_sub_i32 s6, s51, 64
	s_and_b32 s6, s6, 0x1f80
	s_lshl_b32 s8, s6, 1
	v_lshl_add_u64 v[254:255], v[214:215], 0, s[8:9]
	global_load_dwordx4 v[196:199], v[254:255], off
	v_add_co_u32_e32 v254, vcc, 0x100000, v254
	s_nop 1
	v_addc_co_u32_e32 v255, vcc, 0, v255, vcc
	global_load_dwordx4 v[200:203], v[254:255], off
	v_exp_f32_e32 v172, v92
	v_exp_f32_e32 v173, v93
	s_waitcnt lgkmcnt(6)
	v_mfma_f32_32x32x16_bf16 v[144:159], v[112:115], v[176:179], v[16:31]
	v_exp_f32_e32 v174, v94
	v_exp_f32_e32 v175, v95
	s_waitcnt lgkmcnt(5)
	v_mfma_f32_32x32x16_bf16 v[144:159], v[128:131], v[180:183], v[144:159]
	s_waitcnt lgkmcnt(4)
	v_mfma_f32_32x32x16_bf16 v[112:127], v[132:135], v[176:179], v[16:31]
	ds_read_b128 v[128:131], v213 offset:9280
	ds_read_b128 v[132:135], v213 offset:9312
	ds_read_b128 v[140:143], v213 offset:13888
	ds_read_b128 v[228:231], v213 offset:13920
	ds_read_b128 v[160:163], v208 offset:18464
	s_waitcnt lgkmcnt(4)
	v_mfma_f32_32x32x16_bf16 v[144:159], v[128:131], v[184:187], v[144:159]
	v_exp_f32_e32 v128, v96
	v_exp_f32_e32 v129, v97
	v_exp_f32_e32 v130, v98
	v_exp_f32_e32 v131, v99
	ds_read_b128 v[96:99], v208 offset:18432
	s_waitcnt lgkmcnt(4)
	v_mfma_f32_32x32x16_bf16 v[144:159], v[132:135], v[188:191], v[144:159]
	v_exp_f32_e32 v132, v100
	v_exp_f32_e32 v133, v101
	v_exp_f32_e32 v134, v102
	v_exp_f32_e32 v135, v103
	v_cvt_pk_bf16_f32 v100, v128, v129
	v_cvt_pk_bf16_f32 v101, v130, v131
	v_cvt_pk_bf16_f32 v102, v132, v133
	v_cvt_pk_bf16_f32 v103, v134, v135
	v_mfma_f32_32x32x16_bf16 v[112:127], v[136:139], v[180:183], v[112:127]
	v_exp_f32_e32 v136, v104
	v_exp_f32_e32 v137, v105
	v_exp_f32_e32 v138, v106
	v_exp_f32_e32 v139, v107
	s_waitcnt lgkmcnt(0)
	v_mfma_f32_32x32x16_bf16 v[64:79], v[96:99], v[100:103], v[64:79]
	ds_read_b128 v[96:99], v208 offset:23040
	ds_read_b128 v[164:167], v208 offset:23072
	s_waitcnt lgkmcnt(1)
	v_mfma_f32_32x32x16_bf16 v[48:63], v[96:99], v[100:103], v[48:63]
	ds_read_b128 v[96:99], v208 offset:27648
	ds_read_b128 v[168:171], v208 offset:27680
	ds_read_b128 v[104:107], v208 offset:32288
	s_waitcnt lgkmcnt(2)
	v_mfma_f32_32x32x16_bf16 v[32:47], v[96:99], v[100:103], v[32:47]
	ds_read_b128 v[96:99], v208 offset:32256
	v_mfma_f32_32x32x16_bf16 v[112:127], v[140:143], v[184:187], v[112:127]
	v_exp_f32_e32 v140, v108
	v_exp_f32_e32 v141, v109
	v_exp_f32_e32 v142, v110
	v_exp_f32_e32 v143, v111
	s_waitcnt lgkmcnt(0)
	v_mfma_f32_32x32x16_bf16 v[0:15], v[96:99], v[100:103], v[0:15]
	v_cvt_pk_bf16_f32 v96, v136, v137
	v_cvt_pk_bf16_f32 v97, v138, v139
	v_cvt_pk_bf16_f32 v98, v140, v141
	v_cvt_pk_bf16_f32 v99, v142, v143
	s_nop 1
	v_mfma_f32_32x32x16_bf16 v[64:79], v[160:163], v[96:99], v[64:79]
	v_exp_f32_e32 v160, v80
	v_exp_f32_e32 v161, v81
	v_exp_f32_e32 v162, v82
	v_exp_f32_e32 v163, v83
	ds_read_b128 v[80:83], v208 offset:18496
	v_mfma_f32_32x32x16_bf16 v[48:63], v[164:167], v[96:99], v[48:63]
	v_exp_f32_e32 v164, v84
	v_exp_f32_e32 v165, v85
	v_exp_f32_e32 v166, v86
	v_exp_f32_e32 v167, v87
	v_cvt_pk_bf16_f32 v84, v160, v161
	v_cvt_pk_bf16_f32 v85, v162, v163
	v_cvt_pk_bf16_f32 v86, v164, v165
	v_cvt_pk_bf16_f32 v87, v166, v167
	v_mfma_f32_32x32x16_bf16 v[32:47], v[168:171], v[96:99], v[32:47]
	v_exp_f32_e32 v168, v88
	v_exp_f32_e32 v169, v89
	v_exp_f32_e32 v170, v90
	v_exp_f32_e32 v171, v91
	v_mfma_f32_32x32x16_bf16 v[0:15], v[104:107], v[96:99], v[0:15]
	ds_read_b128 v[96:99], v208 offset:18528
	s_waitcnt lgkmcnt(1)
	v_mfma_f32_32x32x16_bf16 v[64:79], v[80:83], v[84:87], v[64:79]
	ds_read_b128 v[80:83], v208 offset:23104
	ds_read_b128 v[100:103], v208 offset:23136
	s_waitcnt lgkmcnt(1)
	v_mfma_f32_32x32x16_bf16 v[48:63], v[80:83], v[84:87], v[48:63]
	ds_read_b128 v[80:83], v208 offset:27712
	ds_read_b128 v[104:107], v208 offset:27744
	ds_read_b128 v[88:91], v208 offset:32352
	s_waitcnt lgkmcnt(2)
	v_mfma_f32_32x32x16_bf16 v[32:47], v[80:83], v[84:87], v[32:47]
	ds_read_b128 v[80:83], v208 offset:32320
	s_waitcnt lgkmcnt(0)
	s_barrier
	v_mfma_f32_32x32x16_bf16 v[0:15], v[80:83], v[84:87], v[0:15]
	v_cvt_pk_bf16_f32 v80, v168, v169
	v_cvt_pk_bf16_f32 v81, v170, v171
	v_cvt_pk_bf16_f32 v82, v172, v173
	v_cvt_pk_bf16_f32 v83, v174, v175
	s_nop 1
	v_mfma_f32_32x32x16_bf16 v[64:79], v[96:99], v[80:83], v[64:79]
	v_mfma_f32_32x32x16_bf16 v[48:63], v[100:103], v[80:83], v[48:63]
	v_mfma_f32_32x32x16_bf16 v[32:47], v[104:107], v[80:83], v[32:47]
	v_mfma_f32_32x32x16_bf16 v[0:15], v[88:91], v[80:83], v[0:15]
	v_mfma_f32_32x32x16_bf16 v[112:127], v[228:231], v[188:191], v[112:127]
	ds_read_b128 v[80:83], v213
	ds_read_b128 v[228:231], v213 offset:32
	ds_read_b128 v[232:235], v213 offset:4608
	ds_read_b128 v[236:239], v213 offset:4640
	s_waitcnt vmcnt(0)
	ds_write_b128 v211, v[192:195] offset:9216
	s_waitcnt vmcnt(1)
	ds_write_b128 v210, v[196:199] offset:18432
	s_waitcnt vmcnt(0)
	ds_write_b128 v212, v[200:203] offset:18432
	s_and_b32 s8, s52, 0x7e000
	s_lshl_b32 s8, s8, 1
	v_lshl_add_u64 v[254:255], v[216:217], 0, s[8:9]
	global_load_dwordx4 v[192:195], v[254:255], off
	s_and_b32 s6, s51, 0x1fc0
	s_lshl_b32 s8, s6, 1
	v_lshl_add_u64 v[254:255], v[214:215], 0, s[8:9]
	global_load_dwordx4 v[196:199], v[254:255], off
	v_add_co_u32_e32 v254, vcc, 0x100000, v254
	s_nop 1
	v_addc_co_u32_e32 v255, vcc, 0, v255, vcc
	global_load_dwordx4 v[200:203], v[254:255], off
	s_waitcnt lgkmcnt(6)
	v_mfma_f32_32x32x16_bf16 v[96:111], v[80:83], v[176:179], v[16:31]
	s_waitcnt lgkmcnt(4)
	v_mfma_f32_32x32x16_bf16 v[80:95], v[232:235], v[176:179], v[16:31]
	v_mfma_f32_32x32x16_bf16 v[96:111], v[228:231], v[180:183], v[96:111]
	ds_read_b128 v[228:231], v213 offset:64
	ds_read_b128 v[232:235], v213 offset:96
	s_waitcnt lgkmcnt(5)
	v_mfma_f32_32x32x16_bf16 v[80:95], v[236:239], v[180:183], v[80:95]
	s_waitcnt lgkmcnt(1)
	v_mfma_f32_32x32x16_bf16 v[96:111], v[228:231], v[184:187], v[96:111]
	ds_read_b128 v[228:231], v213 offset:4672
	ds_read_b128 v[236:239], v213 offset:4704
	s_waitcnt lgkmcnt(1)
	v_mfma_f32_32x32x16_bf16 v[80:95], v[228:231], v[184:187], v[80:95]
	v_mfma_f32_32x32x16_bf16 v[96:111], v[232:235], v[188:191], v[96:111]
	s_waitcnt lgkmcnt(0)
	v_mfma_f32_32x32x16_bf16 v[80:95], v[236:239], v[188:191], v[80:95]
	v_exp_f32_e32 v219, v144
	v_exp_f32_e32 v225, v145
	v_exp_f32_e32 v227, v146
	v_exp_f32_e32 v248, v147
	ds_read_b128 v[144:147], v208 offset:36864
	v_exp_f32_e32 v240, v148
	v_exp_f32_e32 v242, v149
	v_exp_f32_e32 v244, v150
	v_exp_f32_e32 v246, v151
	v_cvt_pk_bf16_f32 v148, v219, v225
	v_cvt_pk_bf16_f32 v149, v227, v248
	v_cvt_pk_bf16_f32 v150, v240, v242
	v_cvt_pk_bf16_f32 v151, v244, v246
	ds_read_b128 v[228:231], v208 offset:36896
	ds_read_b128 v[232:235], v208 offset:41472
	s_waitcnt lgkmcnt(2)
	v_mfma_f32_32x32x16_bf16 v[64:79], v[144:147], v[148:151], v[64:79]
	v_add_f32_e32 v128, v129, v128
	v_add_f32_e32 v129, v161, v160
	ds_read_b128 v[144:147], v208 offset:46080
	ds_read_b128 v[236:239], v208 offset:41504
	v_add_f32_e32 v128, v130, v128
	v_add_f32_e32 v129, v162, v129
	v_add_f32_e32 v128, v131, v128
	v_add_f32_e32 v129, v163, v129
	s_waitcnt lgkmcnt(2)
	v_mfma_f32_32x32x16_bf16 v[48:63], v[232:235], v[148:151], v[48:63]
	v_add_f32_e32 v132, v132, v128
	v_add_f32_e32 v233, v164, v129
	ds_read_b128 v[128:131], v208 offset:50688
	ds_read_b128 v[160:163], v208 offset:46112
	v_exp_f32_e32 v152, v152
	v_exp_f32_e32 v164, v153
	v_exp_f32_e32 v154, v154
	v_exp_f32_e32 v232, v155
	s_waitcnt lgkmcnt(3)
	v_mfma_f32_32x32x16_bf16 v[32:47], v[144:147], v[148:151], v[32:47]
	v_exp_f32_e32 v156, v156
	ds_read_b128 v[144:147], v208 offset:50720
	v_add_f32_e32 v132, v133, v132
	v_add_f32_e32 v133, v165, v233
	v_add_f32_e32 v133, v166, v133
	v_exp_f32_e32 v166, v112
	v_add_f32_e32 v132, v134, v132
	s_waitcnt lgkmcnt(2)
	v_mfma_f32_32x32x16_bf16 v[0:15], v[128:131], v[148:151], v[0:15]
	v_exp_f32_e32 v148, v157
	v_exp_f32_e32 v150, v158
	v_exp_f32_e32 v158, v159
	v_cvt_pk_bf16_f32 v128, v152, v164
	v_cvt_pk_bf16_f32 v129, v154, v232
	v_cvt_pk_bf16_f32 v130, v156, v148
	v_cvt_pk_bf16_f32 v131, v150, v158
	v_add_f32_e32 v132, v135, v132
	v_add_f32_e32 v133, v167, v133
	s_waitcnt lgkmcnt(1)
; template <int DQK, int DV>
; __device__ __forceinline__ void attn_pass(const bf16_t* __restrict__ qh, const bf16_t* __restrict__ kh, const bf16_t* __restrict__ vth, int q0, char* smem, f32x16 (&o)[DV / 32], float kmax, int wvp) {
;     ...
; #pragma unroll
;   for (int ks = 0; ks < NKS; ++ks) asm volatile("" :: "v"(qf[ks]));
; #pragma unroll 1
;   for (int kt = 0; kt < NT; kt += 2) {
;     STEP(sA, sB, kt);
;     STEP(sB, sA, kt + 1);
;   }
	v_mfma_f32_32x32x16_bf16 v[32:47], v[160:163], v[128:131], v[32:47]
	v_exp_f32_e32 v160, v113
	v_exp_f32_e32 v161, v114
	v_exp_f32_e32 v162, v115
	ds_read_b128 v[112:115], v208 offset:36928
	v_add_f32_e32 v132, v136, v132
	v_add_f32_e32 v133, v168, v133
	v_exp_f32_e32 v241, v116
	v_mfma_f32_32x32x16_bf16 v[64:79], v[228:231], v[128:131], v[64:79]
	v_exp_f32_e32 v243, v117
	v_exp_f32_e32 v245, v118
	v_exp_f32_e32 v247, v119
	v_add_f32_e32 v132, v137, v132
	v_add_f32_e32 v133, v169, v133
	v_add_f32_e32 v132, v138, v132
	v_add_f32_e32 v133, v170, v133
	v_mfma_f32_32x32x16_bf16 v[48:63], v[236:239], v[128:131], v[48:63]
	v_add_f32_e32 v136, v139, v132
	v_add_f32_e32 v137, v171, v133
	v_cvt_pk_bf16_f32 v116, v166, v160
	v_cvt_pk_bf16_f32 v117, v161, v162
	v_cvt_pk_bf16_f32 v118, v241, v243
	v_cvt_pk_bf16_f32 v119, v245, v247
	v_exp_f32_e32 v153, v120
	s_waitcnt lgkmcnt(1)
	v_mfma_f32_32x32x16_bf16 v[0:15], v[144:147], v[128:131], v[0:15]
	ds_read_b128 v[128:131], v208 offset:41536
	ds_read_b128 v[132:135], v208 offset:36960
	v_exp_f32_e32 v165, v121
	v_add_f32_e32 v120, v225, v219
	v_add_f32_e32 v121, v160, v166
	v_add_f32_e32 v120, v227, v120
	s_waitcnt lgkmcnt(2)
	v_mfma_f32_32x32x16_bf16 v[64:79], v[112:115], v[116:119], v[64:79]
	v_add_f32_e32 v112, v140, v136
	v_add_f32_e32 v113, v172, v137
	v_add_f32_e32 v112, v141, v112
	v_add_f32_e32 v140, v173, v113
	v_add_f32_e32 v141, v142, v112
	ds_read_b128 v[112:115], v208 offset:46144
	ds_read_b128 v[136:139], v208 offset:41568
	v_add_f32_e32 v121, v161, v121
	s_waitcnt lgkmcnt(3)
	v_mfma_f32_32x32x16_bf16 v[48:63], v[128:131], v[116:119], v[48:63]
	v_add_f32_e32 v128, v174, v140
	v_add_f32_e32 v129, v143, v141
	v_add_f32_e32 v128, v175, v128
	v_add_f32_e32 v128, v129, v128
	v_add_f32_e32 v144, v218, v128
	ds_read_b128 v[128:131], v208 offset:50752
	ds_read_b128 v[140:143], v208 offset:46176
	v_add_f32_e32 v120, v248, v120
	s_waitcnt lgkmcnt(3)
	v_mfma_f32_32x32x16_bf16 v[32:47], v[112:115], v[116:119], v[32:47]
	ds_read_b128 v[112:115], v208 offset:50784
	v_add_f32_e32 v121, v162, v121
	v_add_f32_e64 v120, v240, v120
	v_add_f32_e64 v121, v241, v121
	v_exp_f32_e32 v155, v122
	v_exp_f32_e32 v233, v123
	v_exp_f32_e32 v157, v124
	v_exp_f32_e32 v149, v125
	s_waitcnt lgkmcnt(2)
	v_mfma_f32_32x32x16_bf16 v[0:15], v[128:131], v[116:119], v[0:15]
	v_exp_f32_e32 v151, v126
	v_exp_f32_e32 v159, v127
	v_add_f32_e32 v120, v242, v120
	v_add_f32_e32 v121, v243, v121
	v_cvt_pk_bf16_f32 v116, v153, v165
	v_add_f32_e32 v120, v244, v120
	v_add_f32_e32 v121, v245, v121
	v_cvt_pk_bf16_f32 v117, v155, v233
	v_add_f32_e32 v120, v246, v120
	v_add_f32_e32 v121, v247, v121
	v_cvt_pk_bf16_f32 v118, v157, v149
	v_add_f32_e32 v120, v152, v120
	v_add_f32_e32 v121, v153, v121
	v_cvt_pk_bf16_f32 v119, v151, v159
	v_add_f32_e32 v120, v164, v120
	v_add_f32_e32 v121, v165, v121
	s_add_i32 s53, s53, 2
	v_mfma_f32_32x32x16_bf16 v[64:79], v[132:135], v[116:119], v[64:79]
	v_add_f32_e64 v120, v154, v120
	v_add_f32_e64 v121, v155, v121
	s_addk_i32 s52, 0x2000
	v_add_f32_e64 v120, v232, v120
	v_add_f32_e64 v121, v233, v121
	v_add_f32_e32 v120, v156, v120
	v_add_f32_e32 v121, v157, v121
	s_addk_i32 s51, 0x80
	v_add_f32_e32 v120, v148, v120
	v_add_f32_e32 v121, v149, v121
	v_mfma_f32_32x32x16_bf16 v[48:63], v[136:139], v[116:119], v[48:63]
	v_add_f32_e64 v120, v150, v120
	v_add_f32_e64 v121, v151, v121
	v_add_f32_e64 v120, v158, v120
	v_add_f32_e64 v121, v159, v121
	v_add_f32_e32 v120, v120, v121
	v_add_f32_e32 v218, v144, v120
	s_waitcnt lgkmcnt(1)
	v_mfma_f32_32x32x16_bf16 v[32:47], v[140:143], v[116:119], v[32:47]
	s_waitcnt lgkmcnt(0)
	v_mfma_f32_32x32x16_bf16 v[0:15], v[112:115], v[116:119], v[0:15]
	s_cmpk_lt_u32 s53, 0x7c
	s_cbranch_scc1 .Lfast_e1
	s_branch .LBB0_578

.Lfast_e2:
	s_barrier
	ds_read_b128 v[112:115], v225 offset:9216
	ds_read_b128 v[128:131], v225 offset:9248
	ds_read_b128 v[132:135], v225 offset:13824
	ds_read_b128 v[136:139], v225 offset:13856
	s_waitcnt vmcnt(0)
	ds_write_b128 v215, v[192:195]
	s_waitcnt vmcnt(1)
	ds_write_b128 v212, v[196:199] offset:36864
	s_waitcnt vmcnt(0)
	ds_write_b128 v214, v[200:203] offset:36864
	s_add_i32 s4, s37, 0xfffff000
	s_and_b32 s4, s4, 0x7f000
	s_lshl_b32 s8, s4, 1
	v_lshl_add_u64 v[254:255], v[218:219], 0, s[8:9]
	global_load_dwordx4 v[192:195], v[254:255], off
	s_sub_i32 s6, s19, 64
	s_and_b32 s6, s6, 0x1f80
	s_lshl_b32 s8, s6, 1
	v_lshl_add_u64 v[254:255], v[216:217], 0, s[8:9]
	global_load_dwordx4 v[196:199], v[254:255], off
	v_add_co_u32_e32 v254, vcc, 0x100000, v254
	s_nop 1
	v_addc_co_u32_e32 v255, vcc, 0, v255, vcc
	global_load_dwordx4 v[200:203], v[254:255], off
	v_exp_f32_e32 v172, v92
	v_exp_f32_e32 v173, v93
	s_waitcnt lgkmcnt(6)
	v_mfma_f32_32x32x16_bf16 v[144:159], v[112:115], v[176:179], v[64:79]
	v_exp_f32_e32 v174, v94
	v_exp_f32_e32 v175, v95
	s_waitcnt lgkmcnt(5)
	v_mfma_f32_32x32x16_bf16 v[144:159], v[128:131], v[180:183], v[144:159]
	s_waitcnt lgkmcnt(4)
	v_mfma_f32_32x32x16_bf16 v[112:127], v[132:135], v[176:179], v[64:79]
	ds_read_b128 v[128:131], v225 offset:9280
	ds_read_b128 v[132:135], v225 offset:9312
	ds_read_b128 v[140:143], v225 offset:13888
	ds_read_b128 v[228:231], v225 offset:13920
	ds_read_b128 v[160:163], v208 offset:18464
	s_waitcnt lgkmcnt(4)
	v_mfma_f32_32x32x16_bf16 v[144:159], v[128:131], v[184:187], v[144:159]
	v_exp_f32_e32 v128, v96
	v_exp_f32_e32 v129, v97
	v_exp_f32_e32 v130, v98
	v_exp_f32_e32 v131, v99
	ds_read_b128 v[96:99], v208 offset:18432
	s_waitcnt lgkmcnt(4)
	v_mfma_f32_32x32x16_bf16 v[144:159], v[132:135], v[188:191], v[144:159]
	v_exp_f32_e32 v132, v100
	v_exp_f32_e32 v133, v101
	v_exp_f32_e32 v134, v102
	v_exp_f32_e32 v135, v103
	v_cvt_pk_bf16_f32 v100, v128, v129
	v_cvt_pk_bf16_f32 v101, v130, v131
	v_cvt_pk_bf16_f32 v102, v132, v133
	v_cvt_pk_bf16_f32 v103, v134, v135
	v_mfma_f32_32x32x16_bf16 v[112:127], v[136:139], v[180:183], v[112:127]
	v_exp_f32_e32 v136, v104
	v_exp_f32_e32 v137, v105
	v_exp_f32_e32 v138, v106
	v_exp_f32_e32 v139, v107
	s_waitcnt lgkmcnt(0)
	v_mfma_f32_32x32x16_bf16 v[0:15], v[96:99], v[100:103], v[0:15]
	ds_read_b128 v[96:99], v208 offset:23040
	ds_read_b128 v[164:167], v208 offset:23072
	s_waitcnt lgkmcnt(1)
	v_mfma_f32_32x32x16_bf16 v[48:63], v[96:99], v[100:103], v[48:63]
	ds_read_b128 v[96:99], v208 offset:27648
	ds_read_b128 v[168:171], v208 offset:27680
	ds_read_b128 v[104:107], v208 offset:32288
	s_waitcnt lgkmcnt(2)
	v_mfma_f32_32x32x16_bf16 v[32:47], v[96:99], v[100:103], v[32:47]
	ds_read_b128 v[96:99], v208 offset:32256
	v_mfma_f32_32x32x16_bf16 v[112:127], v[140:143], v[184:187], v[112:127]
	v_exp_f32_e32 v140, v108
	v_exp_f32_e32 v141, v109
	v_exp_f32_e32 v142, v110
	v_exp_f32_e32 v143, v111
	s_waitcnt lgkmcnt(0)
	v_mfma_f32_32x32x16_bf16 v[16:31], v[96:99], v[100:103], v[16:31]
	v_cvt_pk_bf16_f32 v96, v136, v137
	v_cvt_pk_bf16_f32 v97, v138, v139
	v_cvt_pk_bf16_f32 v98, v140, v141
	v_cvt_pk_bf16_f32 v99, v142, v143
	s_nop 1
	v_mfma_f32_32x32x16_bf16 v[0:15], v[160:163], v[96:99], v[0:15]
	v_exp_f32_e32 v160, v80
	v_exp_f32_e32 v161, v81
	v_exp_f32_e32 v162, v82
	v_exp_f32_e32 v163, v83
	ds_read_b128 v[80:83], v208 offset:18496
	v_mfma_f32_32x32x16_bf16 v[48:63], v[164:167], v[96:99], v[48:63]
	v_exp_f32_e32 v164, v84
	v_exp_f32_e32 v165, v85
	v_exp_f32_e32 v166, v86
	v_exp_f32_e32 v167, v87
	v_cvt_pk_bf16_f32 v84, v160, v161
	v_cvt_pk_bf16_f32 v85, v162, v163
	v_cvt_pk_bf16_f32 v86, v164, v165
	v_cvt_pk_bf16_f32 v87, v166, v167
	v_mfma_f32_32x32x16_bf16 v[32:47], v[168:171], v[96:99], v[32:47]
	v_exp_f32_e32 v168, v88
	v_exp_f32_e32 v169, v89
	v_exp_f32_e32 v170, v90
	v_exp_f32_e32 v171, v91
	v_mfma_f32_32x32x16_bf16 v[16:31], v[104:107], v[96:99], v[16:31]
	ds_read_b128 v[96:99], v208 offset:18528
	s_waitcnt lgkmcnt(1)
	v_mfma_f32_32x32x16_bf16 v[0:15], v[80:83], v[84:87], v[0:15]
	ds_read_b128 v[80:83], v208 offset:23104
	ds_read_b128 v[100:103], v208 offset:23136
	s_waitcnt lgkmcnt(1)
	v_mfma_f32_32x32x16_bf16 v[48:63], v[80:83], v[84:87], v[48:63]
	ds_read_b128 v[80:83], v208 offset:27712
	ds_read_b128 v[104:107], v208 offset:27744
	ds_read_b128 v[88:91], v208 offset:32352
	s_waitcnt lgkmcnt(2)
	v_mfma_f32_32x32x16_bf16 v[32:47], v[80:83], v[84:87], v[32:47]
	ds_read_b128 v[80:83], v208 offset:32320
	s_waitcnt lgkmcnt(0)
	s_barrier
	v_mfma_f32_32x32x16_bf16 v[16:31], v[80:83], v[84:87], v[16:31]
	v_cvt_pk_bf16_f32 v80, v168, v169
	v_cvt_pk_bf16_f32 v81, v170, v171
	v_cvt_pk_bf16_f32 v82, v172, v173
	v_cvt_pk_bf16_f32 v83, v174, v175
	s_nop 1
	v_mfma_f32_32x32x16_bf16 v[0:15], v[96:99], v[80:83], v[0:15]
	v_mfma_f32_32x32x16_bf16 v[48:63], v[100:103], v[80:83], v[48:63]
	v_mfma_f32_32x32x16_bf16 v[32:47], v[104:107], v[80:83], v[32:47]
	v_mfma_f32_32x32x16_bf16 v[16:31], v[88:91], v[80:83], v[16:31]
	v_mfma_f32_32x32x16_bf16 v[112:127], v[228:231], v[188:191], v[112:127]
	ds_read_b128 v[80:83], v225
	ds_read_b128 v[228:231], v225 offset:32
	ds_read_b128 v[232:235], v225 offset:4608
	ds_read_b128 v[236:239], v225 offset:4640
	s_waitcnt vmcnt(0)
	ds_write_b128 v215, v[192:195] offset:9216
	s_waitcnt vmcnt(1)
	ds_write_b128 v212, v[196:199] offset:18432
	s_waitcnt vmcnt(0)
	ds_write_b128 v214, v[200:203] offset:18432
	s_and_b32 s8, s37, 0x7e000
	s_lshl_b32 s8, s8, 1
	v_lshl_add_u64 v[254:255], v[218:219], 0, s[8:9]
	global_load_dwordx4 v[192:195], v[254:255], off
	s_and_b32 s6, s19, 0x1fc0
	s_lshl_b32 s8, s6, 1
	v_lshl_add_u64 v[254:255], v[216:217], 0, s[8:9]
	global_load_dwordx4 v[196:199], v[254:255], off
	v_add_co_u32_e32 v254, vcc, 0x100000, v254
	s_nop 1
	v_addc_co_u32_e32 v255, vcc, 0, v255, vcc
	global_load_dwordx4 v[200:203], v[254:255], off
	s_waitcnt lgkmcnt(6)
	v_mfma_f32_32x32x16_bf16 v[96:111], v[80:83], v[176:179], v[64:79]
	s_waitcnt lgkmcnt(4)
	v_mfma_f32_32x32x16_bf16 v[80:95], v[232:235], v[176:179], v[64:79]
	v_mfma_f32_32x32x16_bf16 v[96:111], v[228:231], v[180:183], v[96:111]
	ds_read_b128 v[228:231], v225 offset:64
	ds_read_b128 v[232:235], v225 offset:96
	s_waitcnt lgkmcnt(5)
	v_mfma_f32_32x32x16_bf16 v[80:95], v[236:239], v[180:183], v[80:95]
	s_waitcnt lgkmcnt(1)
	v_mfma_f32_32x32x16_bf16 v[96:111], v[228:231], v[184:187], v[96:111]
	ds_read_b128 v[228:231], v225 offset:4672
	ds_read_b128 v[236:239], v225 offset:4704
	s_waitcnt lgkmcnt(1)
	v_mfma_f32_32x32x16_bf16 v[80:95], v[228:231], v[184:187], v[80:95]
	v_mfma_f32_32x32x16_bf16 v[96:111], v[232:235], v[188:191], v[96:111]
	s_waitcnt lgkmcnt(0)
	v_mfma_f32_32x32x16_bf16 v[80:95], v[236:239], v[188:191], v[80:95]
	v_exp_f32_e32 v227, v144
	v_exp_f32_e32 v248, v145
	v_exp_f32_e32 v249, v146
	v_exp_f32_e32 v250, v147
	ds_read_b128 v[144:147], v208 offset:36864
	v_exp_f32_e32 v240, v148
	v_exp_f32_e32 v242, v149
	v_exp_f32_e32 v244, v150
	v_exp_f32_e32 v246, v151
	v_cvt_pk_bf16_f32 v148, v227, v248
	v_cvt_pk_bf16_f32 v149, v249, v250
	v_cvt_pk_bf16_f32 v150, v240, v242
	v_cvt_pk_bf16_f32 v151, v244, v246
	ds_read_b128 v[228:231], v208 offset:36896
	ds_read_b128 v[232:235], v208 offset:41472
	s_waitcnt lgkmcnt(2)
	v_mfma_f32_32x32x16_bf16 v[0:15], v[144:147], v[148:151], v[0:15]
	v_add_f32_e32 v128, v129, v128
	v_add_f32_e32 v129, v161, v160
	ds_read_b128 v[144:147], v208 offset:46080
	ds_read_b128 v[236:239], v208 offset:41504
	v_add_f32_e32 v128, v130, v128
	v_add_f32_e32 v129, v162, v129
	v_add_f32_e32 v128, v131, v128
	v_add_f32_e32 v129, v163, v129
	s_waitcnt lgkmcnt(2)
	v_mfma_f32_32x32x16_bf16 v[48:63], v[232:235], v[148:151], v[48:63]
	v_add_f32_e32 v132, v132, v128
	v_add_f32_e32 v233, v164, v129
	ds_read_b128 v[128:131], v208 offset:50688
	ds_read_b128 v[160:163], v208 offset:46112
	v_exp_f32_e32 v152, v152
	v_exp_f32_e32 v164, v153
	v_exp_f32_e32 v154, v154
	v_exp_f32_e32 v232, v155
	s_waitcnt lgkmcnt(3)
	v_mfma_f32_32x32x16_bf16 v[32:47], v[144:147], v[148:151], v[32:47]
	v_exp_f32_e32 v156, v156
	ds_read_b128 v[144:147], v208 offset:50720
	v_add_f32_e32 v132, v133, v132
	v_add_f32_e32 v133, v165, v233
	v_add_f32_e32 v133, v166, v133
	v_exp_f32_e32 v166, v112
	v_add_f32_e32 v132, v134, v132
	s_waitcnt lgkmcnt(2)
	v_mfma_f32_32x32x16_bf16 v[16:31], v[128:131], v[148:151], v[16:31]
	v_exp_f32_e32 v148, v157
	v_exp_f32_e32 v150, v158
	v_exp_f32_e32 v158, v159
	v_cvt_pk_bf16_f32 v128, v152, v164
	v_cvt_pk_bf16_f32 v129, v154, v232
	v_cvt_pk_bf16_f32 v130, v156, v148
	v_cvt_pk_bf16_f32 v131, v150, v158
	v_add_f32_e32 v132, v135, v132
	v_add_f32_e32 v133, v167, v133
	s_waitcnt lgkmcnt(1)
; template <int DQK, int DV>
; __device__ __forceinline__ void attn_pass(const bf16_t* __restrict__ qh, const bf16_t* __restrict__ kh, const bf16_t* __restrict__ vth, int q0, char* smem, f32x16 (&o)[DV / 32], float kmax, int wvp) {
;     ...
; #pragma unroll
;   for (int ks = 0; ks < NKS; ++ks) asm volatile("" :: "v"(qf[ks]));
; #pragma unroll 1
;   for (int kt = 0; kt < NT; kt += 2) {
;     STEP(sA, sB, kt);
;     STEP(sB, sA, kt + 1);
;   }
	v_mfma_f32_32x32x16_bf16 v[32:47], v[160:163], v[128:131], v[32:47]
	v_exp_f32_e32 v160, v113
	v_exp_f32_e32 v161, v114
	v_exp_f32_e32 v162, v115
	ds_read_b128 v[112:115], v208 offset:36928
	v_add_f32_e32 v132, v136, v132
	v_add_f32_e32 v133, v168, v133
	v_exp_f32_e32 v241, v116
	v_mfma_f32_32x32x16_bf16 v[0:15], v[228:231], v[128:131], v[0:15]
	v_exp_f32_e32 v243, v117
	v_exp_f32_e32 v245, v118
	v_exp_f32_e32 v247, v119
	v_add_f32_e32 v132, v137, v132
	v_add_f32_e32 v133, v169, v133
	v_add_f32_e32 v132, v138, v132
	v_add_f32_e32 v133, v170, v133
	v_mfma_f32_32x32x16_bf16 v[48:63], v[236:239], v[128:131], v[48:63]
	v_add_f32_e32 v136, v139, v132
	v_add_f32_e32 v137, v171, v133
	v_cvt_pk_bf16_f32 v116, v166, v160
	v_cvt_pk_bf16_f32 v117, v161, v162
	v_cvt_pk_bf16_f32 v118, v241, v243
	v_cvt_pk_bf16_f32 v119, v245, v247
	v_exp_f32_e32 v153, v120
	s_waitcnt lgkmcnt(1)
	v_mfma_f32_32x32x16_bf16 v[16:31], v[144:147], v[128:131], v[16:31]
	ds_read_b128 v[128:131], v208 offset:41536
	ds_read_b128 v[132:135], v208 offset:36960
	v_exp_f32_e32 v165, v121
	v_add_f32_e32 v120, v248, v227
	v_add_f32_e32 v121, v160, v166
	v_add_f32_e32 v120, v249, v120
	s_waitcnt lgkmcnt(2)
	v_mfma_f32_32x32x16_bf16 v[0:15], v[112:115], v[116:119], v[0:15]
	v_add_f32_e32 v112, v140, v136
	v_add_f32_e32 v113, v172, v137
	v_add_f32_e32 v112, v141, v112
	v_add_f32_e32 v140, v173, v113
	v_add_f32_e32 v141, v142, v112
	ds_read_b128 v[112:115], v208 offset:46144
	ds_read_b128 v[136:139], v208 offset:41568
	v_add_f32_e32 v121, v161, v121
	s_waitcnt lgkmcnt(3)
	v_mfma_f32_32x32x16_bf16 v[48:63], v[128:131], v[116:119], v[48:63]
	v_add_f32_e32 v128, v174, v140
	v_add_f32_e32 v129, v143, v141
	v_add_f32_e32 v128, v175, v128
	v_add_f32_e32 v128, v129, v128
	v_add_f32_e32 v144, v213, v128
	ds_read_b128 v[128:131], v208 offset:50752
	ds_read_b128 v[140:143], v208 offset:46176
	v_add_f32_e32 v120, v250, v120
	s_waitcnt lgkmcnt(3)
	v_mfma_f32_32x32x16_bf16 v[32:47], v[112:115], v[116:119], v[32:47]
	ds_read_b128 v[112:115], v208 offset:50784
	v_add_f32_e32 v121, v162, v121
	v_add_f32_e64 v120, v240, v120
	v_add_f32_e64 v121, v241, v121
	v_exp_f32_e32 v155, v122
	v_exp_f32_e32 v233, v123
	v_exp_f32_e32 v157, v124
	v_exp_f32_e32 v149, v125
	s_waitcnt lgkmcnt(2)
	v_mfma_f32_32x32x16_bf16 v[16:31], v[128:131], v[116:119], v[16:31]
	v_exp_f32_e32 v151, v126
	v_exp_f32_e32 v159, v127
	v_add_f32_e32 v120, v242, v120
	v_add_f32_e32 v121, v243, v121
	v_cvt_pk_bf16_f32 v116, v153, v165
	v_add_f32_e32 v120, v244, v120
	v_add_f32_e32 v121, v245, v121
	v_cvt_pk_bf16_f32 v117, v155, v233
	v_add_f32_e32 v120, v246, v120
	v_add_f32_e32 v121, v247, v121
	v_cvt_pk_bf16_f32 v118, v157, v149
	v_add_f32_e32 v120, v152, v120
	v_add_f32_e32 v121, v153, v121
	v_cvt_pk_bf16_f32 v119, v151, v159
	v_add_f32_e32 v120, v164, v120
	v_add_f32_e32 v121, v165, v121
	s_add_i32 s18, s18, 2
	v_mfma_f32_32x32x16_bf16 v[0:15], v[132:135], v[116:119], v[0:15]
	v_add_f32_e64 v120, v154, v120
	v_add_f32_e64 v121, v155, v121
	s_addk_i32 s37, 0x2000
	v_add_f32_e64 v120, v232, v120
	v_add_f32_e64 v121, v233, v121
	v_add_f32_e32 v120, v156, v120
	v_add_f32_e32 v121, v157, v121
	s_addk_i32 s19, 0x80
	v_add_f32_e32 v120, v148, v120
	v_add_f32_e32 v121, v149, v121
	v_mfma_f32_32x32x16_bf16 v[48:63], v[136:139], v[116:119], v[48:63]
	v_add_f32_e64 v120, v150, v120
	v_add_f32_e64 v121, v151, v121
	v_add_f32_e64 v120, v158, v120
	v_add_f32_e64 v121, v159, v121
	v_add_f32_e32 v120, v120, v121
	v_add_f32_e32 v213, v144, v120
	s_waitcnt lgkmcnt(1)
	v_mfma_f32_32x32x16_bf16 v[32:47], v[140:143], v[116:119], v[32:47]
	s_waitcnt lgkmcnt(0)
	v_mfma_f32_32x32x16_bf16 v[16:31], v[112:115], v[116:119], v[16:31]
	s_cmpk_lt_u32 s18, 0x7c
	s_cbranch_scc1 .Lfast_e2
	s_branch .LBB0_597
